# attention unit prologue: the three priming LDS-DMA tile groups issued right after the Q/K-norm loads (both load latencies overlap)
# baseline (speedup 1.0000x reference)
.LBB0_428:
	s_ashr_i32 s0, s18, 6
	s_add_i32 s4, s0, s19
	s_ashr_i32 s16, s4, 2
	v_mov_b32_e32 v132, v188
	s_ashr_i32 s17, s16, 31
	v_readfirstlane_b32 s34, v132
	s_lshl_b32 s5, s18, 7
	s_bfe_u32 s31, s34, 0x20006
	s_lshl_b64 s[2:3], s[16:17], 13
	s_and_b32 s0, s5, 0x1f80
	s_or_b32 s0, s2, s0
	s_lshl_b32 s2, s31, 5
	v_and_b32_e32 v202, 31, v132
	s_or_b32 s0, s0, s2
	v_or_b32_e32 v176, s0, v202
	v_mad_u64_u32 v[16:17], s[0:1], v176, s20, v[172:173]
	s_lshl_b32 s0, s4, 7
	s_ashr_i32 s30, s34, 8
	s_and_b32 s0, s0, 0x180
	v_mad_i32_i24 v17, s3, v189, v17
	s_lshl_b32 s12, s0, 1
	s_lshl_b32 s0, s30, 6
	v_bfe_u32 v133, v132, 5, 1
	v_lshl_add_u64 v[16:17], v[16:17], 0, s[12:13]
	s_ashr_i32 s1, s0, 31
	v_lshl_add_u64 v[16:17], s[0:1], 1, v[16:17]
	v_lshlrev_b32_e32 v166, 4, v133
	v_lshl_add_u64 v[16:17], v[16:17], 0, v[166:167]
	global_load_dwordx4 v[90:93], v[16:17], off offset:3136
	global_load_dwordx4 v[96:99], v[16:17], off offset:3168
	global_load_dwordx4 v[108:111], v[16:17], off offset:3072
	global_load_dwordx4 v[112:115], v[16:17], off offset:3104
	v_cmp_lt_i32_e32 vcc, v191, v192
	s_or_b32 s0, s2, s5
	s_lshl_b32 s0, s0, 1
	v_cndmask_b32_e32 v16, v190, v191, vcc
	v_lshlrev_b32_e32 v195, 2, v16
	v_and_b32_e32 v16, 32, v132
	global_load_dwordx4 v[40:43], v16, s[62:63] offset:144
	global_load_dwordx4 v[44:47], v16, s[62:63] offset:128
	global_load_dwordx4 v[28:31], v16, s[62:63] offset:208
	global_load_dwordx4 v[36:39], v16, s[62:63] offset:192
	global_load_dwordx4 v[72:75], v16, s[62:63] offset:16
	global_load_dwordx4 v[76:79], v16, s[62:63]
	global_load_dwordx4 v[64:67], v16, s[62:63] offset:80
	global_load_dwordx4 v[68:71], v16, s[62:63] offset:64
	v_lshlrev_b32_e32 v48, 6, v133
	v_and_or_b32 v16, s2, 32, v202
	s_and_b32 s0, s0, 0x3f80
	v_lshl_or_b32 v32, v16, 7, v48
	v_or_b32_e32 v60, s0, v48
	global_load_dwordx4 v[16:19], v32, s[10:11] offset:48
	global_load_dwordx4 v[20:23], v32, s[10:11] offset:32
	global_load_dwordx4 v[24:27], v32, s[10:11] offset:16
	s_nop 0
	global_load_dwordx4 v[32:35], v32, s[10:11]
	s_nop 0
	global_load_dwordx4 v[48:51], v60, s[10:11] offset:48
	global_load_dwordx4 v[52:55], v60, s[10:11] offset:32
	global_load_dwordx4 v[56:59], v60, s[10:11] offset:16
	s_nop 0
	global_load_dwordx4 v[60:63], v60, s[10:11]
	v_mov_b32_e32 v177, s3
	v_lshrrev_b32_e32 v226, 6, v188
	v_lshrrev_b32_e32 v227, 4, v190
	v_and_b32_e32 v228, 15, v190
	v_lshl_add_u32 v229, v226, 3, v227
	v_and_b32_e32 v230, 15, v229
	v_xor_b32_e32 v230, v228, v230
	v_mul_u32_u24_e32 v231, 0x1a00, v229
	v_lshl_add_u32 v181, v230, 4, v231
	v_add_u32_e32 v232, 4, v229
	v_and_b32_e32 v230, 15, v232
	v_xor_b32_e32 v230, v228, v230
	v_mul_u32_u24_e32 v232, 0x1a00, v232
	v_lshl_add_u32 v165, v230, 4, v232
	v_lshlrev_b32_e32 v230, 2, v227
	v_xor_b32_e32 v230, v228, v230
	v_lshl_add_u32 v230, v230, 4, v231
	v_add_u32_e32 v207, 0x400, v230
	v_add_u32_e32 v208, 0x6c00, v230
	s_lshl_b32 s1, s16, 8
	s_add_i32 s1, s1, 0x8000
	s_mul_i32 s2, s1, 0x1a00
	s_add_u32 s22, s8, s12
	s_addc_u32 s23, s9, 0
	s_add_u32 s22, s22, 0x1000
	s_addc_u32 s23, s23, 0
	s_add_u32 s36, s22, s2
	s_addc_u32 s37, s23, 0
	s_lshl_b32 s3, s16, 13
	s_mul_i32 s3, s3, 0x1a00
	s_add_u32 s38, s22, s3
	s_addc_u32 s39, s23, 0
	s_lshr_b32 s17, s34, 6
	s_lshl_b32 s17, s17, 11
	s_add_i32 m0, s17, 0
	s_nop 0
	global_load_lds_dwordx4 v181, s[36:37]
	s_add_i32 m0, s17, 1024
	s_nop 0
	global_load_lds_dwordx4 v165, s[36:37]
	s_add_i32 m0, s17, 16384
	s_nop 0
	global_load_lds_dwordx4 v207, s[36:37]
	s_add_i32 m0, s17, 17408
	s_nop 0
	global_load_lds_dwordx4 v208, s[36:37]
	s_add_u32 s36, s36, 0x68000
	s_addc_u32 s37, s37, 0
	s_add_i32 m0, s17, 32768
	s_nop 0
	global_load_lds_dwordx4 v181, s[36:37]
	s_add_i32 m0, s17, 33792
	s_nop 0
	global_load_lds_dwordx4 v165, s[36:37]
	s_add_i32 m0, s17, 49152
	s_nop 0
	global_load_lds_dwordx4 v207, s[36:37]
	s_add_i32 m0, s17, 50176
	s_nop 0
	global_load_lds_dwordx4 v208, s[36:37]
	s_add_u32 s36, s36, 0x68000
	s_addc_u32 s37, s37, 0
	s_add_i32 m0, s17, 65536
	s_nop 0
	global_load_lds_dwordx4 v181, s[36:37]
	s_add_i32 m0, s17, 66560
	s_nop 0
	global_load_lds_dwordx4 v165, s[36:37]
	s_add_i32 m0, s17, 81920
	s_nop 0
	global_load_lds_dwordx4 v207, s[36:37]
	s_add_i32 m0, s17, 82944
	s_nop 0
	global_load_lds_dwordx4 v208, s[36:37]
	s_add_u32 s36, s36, 0x68000
	s_addc_u32 s37, s37, 0
	v_cmp_gt_i32_e32 vcc, s21, v132
	s_waitcnt vmcnt(31)
	v_lshlrev_b32_e32 v84, 16, v93
	s_waitcnt vmcnt(30)
	v_lshlrev_b32_e32 v80, 16, v99
	v_and_b32_e32 v81, 0xffff0000, v99
	v_lshlrev_b32_e32 v82, 16, v98
	v_and_b32_e32 v83, 0xffff0000, v98
	s_waitcnt vmcnt(29)
	v_lshlrev_b32_e32 v98, 16, v111
	v_and_b32_e32 v99, 0xffff0000, v111
	v_lshlrev_b32_e32 v102, 16, v110
	v_and_b32_e32 v103, 0xffff0000, v110
	v_lshlrev_b32_e32 v110, 16, v108
	v_and_b32_e32 v111, 0xffff0000, v108
	v_lshlrev_b32_e32 v106, 16, v109
	v_and_b32_e32 v107, 0xffff0000, v109
	v_pk_mul_f32 v[148:149], v[110:111], v[110:111]
	v_pk_mul_f32 v[144:145], v[106:107], v[106:107]
	v_add_f32_e32 v148, v148, v149
	v_add_f32_e32 v144, v144, v148
	v_pk_mul_f32 v[142:143], v[102:103], v[102:103]
	v_add_f32_e32 v144, v145, v144
	v_add_f32_e32 v142, v142, v144
	v_pk_mul_f32 v[138:139], v[98:99], v[98:99]
	v_add_f32_e32 v142, v143, v142
	s_waitcnt vmcnt(28)
	v_lshlrev_b32_e32 v108, 16, v112
	v_and_b32_e32 v109, 0xffff0000, v112
	v_add_f32_e32 v138, v138, v142
	v_lshlrev_b32_e32 v104, 16, v113
	v_and_b32_e32 v105, 0xffff0000, v113
	v_pk_mul_f32 v[112:113], v[108:109], v[108:109]
	v_add_f32_e32 v138, v139, v138
	v_add_f32_e32 v112, v112, v138
	v_pk_mul_f32 v[146:147], v[104:105], v[104:105]
	v_add_f32_e32 v112, v113, v112
	v_lshlrev_b32_e32 v100, 16, v114
	v_and_b32_e32 v101, 0xffff0000, v114
	v_add_f32_e32 v112, v146, v112
	v_and_b32_e32 v85, 0xffff0000, v93
	v_lshlrev_b32_e32 v88, 16, v92
	v_and_b32_e32 v89, 0xffff0000, v92
	v_lshlrev_b32_e32 v92, 16, v91
	v_and_b32_e32 v93, 0xffff0000, v91
	v_lshlrev_b32_e32 v86, 16, v97
	v_and_b32_e32 v87, 0xffff0000, v97
	v_lshlrev_b32_e32 v94, 16, v90
	v_and_b32_e32 v95, 0xffff0000, v90
	v_lshlrev_b32_e32 v90, 16, v96
	v_and_b32_e32 v91, 0xffff0000, v96
	v_lshlrev_b32_e32 v96, 16, v115
	v_and_b32_e32 v97, 0xffff0000, v115
	v_pk_mul_f32 v[114:115], v[100:101], v[100:101]
	v_add_f32_e32 v112, v147, v112
	v_add_f32_e32 v112, v114, v112
	v_pk_mul_f32 v[140:141], v[96:97], v[96:97]
	v_add_f32_e32 v112, v115, v112
	v_add_f32_e32 v112, v140, v112
	v_pk_mul_f32 v[134:135], v[94:95], v[94:95]
	v_add_f32_e32 v112, v141, v112
	v_add_f32_e32 v112, v134, v112
	v_pk_mul_f32 v[124:125], v[92:93], v[92:93]
	v_add_f32_e32 v112, v135, v112
	v_add_f32_e32 v112, v124, v112
	v_pk_mul_f32 v[120:121], v[88:89], v[88:89]
	v_add_f32_e32 v112, v125, v112
	v_add_f32_e32 v112, v120, v112
	v_pk_mul_f32 v[116:117], v[84:85], v[84:85]
	v_add_f32_e32 v112, v121, v112
	v_add_f32_e32 v112, v116, v112
	v_pk_mul_f32 v[136:137], v[90:91], v[90:91]
	v_add_f32_e32 v112, v117, v112
	v_add_f32_e32 v112, v136, v112
	v_pk_mul_f32 v[126:127], v[86:87], v[86:87]
	v_add_f32_e32 v112, v137, v112
	v_add_f32_e32 v112, v126, v112
	v_pk_mul_f32 v[122:123], v[82:83], v[82:83]
	v_add_f32_e32 v112, v127, v112
	v_add_f32_e32 v112, v122, v112
	v_pk_mul_f32 v[118:119], v[80:81], v[80:81]
	v_add_f32_e32 v112, v123, v112
	v_add_f32_e32 v112, v118, v112
	v_add_f32_e32 v134, v119, v112
	ds_bpermute_b32 v135, v195, v134
	v_and_b32_e32 v112, 31, v190
	v_lshrrev_b32_e32 v113, 5, v190
	v_lshrrev_b32_e32 v114, 8, v188
	v_lshl_or_b32 v113, v114, 3, v113
	v_and_b32_e32 v115, 15, v112
	v_xor_b32_e32 v113, v113, v115
	v_lshlrev_b32_e32 v112, 8, v112
	v_lshl_add_u32 v178, v113, 4, v112
	v_xor_b32_e32 v116, 2, v113
	v_lshl_add_u32 v128, v116, 4, v112
	v_xor_b32_e32 v116, 4, v113
	v_lshl_add_u32 v130, v116, 4, v112
	v_xor_b32_e32 v116, 6, v113
	v_lshl_add_u32 v131, v116, 4, v112
	v_add_u32_e32 v180, 0x10000, v178
	v_add_u32_e32 v189, 0x10000, v128
	v_add_u32_e32 v191, 0x10000, v130
	v_add_u32_e32 v192, 0x10000, v131
	v_and_b32_e32 v112, 3, v190
	v_bfe_u32 v113, v190, 2, 2
	v_bfe_u32 v114, v190, 4, 1
	v_lshrrev_b32_e32 v115, 5, v190
	v_lshlrev_b32_e32 v115, 10, v115
	v_lshl_add_u32 v115, v113, 8, v115
	v_lshl_add_u32 v115, v114, 5, v115
	v_lshl_add_u32 v115, v112, 3, v115
	v_add_u32_e32 v115, 0x4000, v115
	v_lshl_add_u32 v184, v113, 6, v115
	v_xor_b32_e32 v116, 1, v113
	v_lshl_add_u32 v185, v116, 6, v115
	v_xor_b32_e32 v116, 2, v113
	v_lshl_add_u32 v186, v116, 6, v115
	v_xor_b32_e32 v116, 3, v113
	v_lshl_add_u32 v187, v116, 6, v115
	v_add_u32_e32 v198, 0x10000, v184
	v_add_u32_e32 v199, 0x10000, v185
	v_add_u32_e32 v201, 0x10000, v186
	v_add_u32_e32 v203, 0x10000, v187
	v_mov_b32_e32 v148, 0
	v_mov_b32_e32 v149, 0
	v_mov_b32_e32 v150, 0
	v_mov_b32_e32 v151, 0
	v_lshlrev_b32_e32 v112, 4, v188
	v_add_u32_e32 v112, 0x1e000, v112
	ds_write_b128 v112, v[148:151]
	s_waitcnt vmcnt(12)
	s_waitcnt lgkmcnt(0)
	v_lshrrev_b32_e32 v136, 2, v132
	v_lshlrev_b32_e32 v179, 2, v133
	v_and_or_b32 v133, v136, 3, v179
	v_mul_u32_u24_e32 v204, 0x140, v133
	v_lshlrev_b32_e32 v133, 1, v132
	v_and_b32_e32 v205, 32, v133
	v_add_f32_e32 v133, v134, v135
	v_fmamk_f32 v133, v133, 0x3c800000, v193
	v_mul_f32_e32 v134, 0x4b800000, v133
	v_cmp_gt_f32_e32 vcc, s27, v133
	v_lshlrev_b32_e32 v132, 3, v132
	v_and_b32_e32 v206, 24, v132
	v_cndmask_b32_e32 v133, v133, v134, vcc
	v_rsq_f32_e32 v133, v133
	v_add3_u32 v197, v204, v205, v206
	v_add_u32_e32 v200, 0, v197
	s_lshl_b32 s0, s30, 7
	v_mul_f32_e32 v132, 0x45800000, v133
	v_cndmask_b32_e32 v132, v133, v132, vcc
	v_mul_f32_e32 v132, 0x3e38aa3b, v132
	v_pk_mul_f32 v[68:69], v[68:69], v[132:133] op_sel_hi:[1,0]
	v_pk_mul_f32 v[30:31], v[30:31], v[132:133] op_sel_hi:[1,0]
	v_pk_mul_f32 v[76:77], v[76:77], v[132:133] op_sel_hi:[1,0]
	v_pk_mul_f32 v[68:69], v[68:69], v[108:109]
	v_pk_mul_f32 v[30:31], v[30:31], v[80:81]
	v_mov_b32_e32 v80, v60
	v_mov_b32_e32 v81, v62
	v_mov_b32_e32 v62, v61
	v_pk_mul_f32 v[76:77], v[76:77], v[110:111]
	v_pk_mul_f32 v[70:71], v[70:71], v[132:133] op_sel_hi:[1,0]
	v_pk_mul_f32 v[60:61], v[62:63], v[68:69]
	v_pk_mul_f32 v[68:69], v[80:81], v[68:69]
	v_pk_mul_f32 v[78:79], v[78:79], v[132:133] op_sel_hi:[1,0]
	v_pk_mul_f32 v[70:71], v[70:71], v[104:105]
	v_pk_fma_f32 v[62:63], v[62:63], v[76:77], v[68:69]
	v_mov_b32_e32 v69, v58
	v_mov_b32_e32 v58, v57
	v_pk_mul_f32 v[78:79], v[78:79], v[106:107]
	v_mov_b32_e32 v68, v56
	v_pk_mul_f32 v[56:57], v[58:59], v[70:71]
	v_pk_mul_f32 v[64:65], v[64:65], v[132:133] op_sel_hi:[1,0]
	v_pk_fma_f32 v[56:57], v[68:69], v[78:79], v[56:57] neg_lo:[0,0,1] neg_hi:[0,0,1]
	v_pk_mul_f32 v[68:69], v[68:69], v[70:71]
	v_pk_mul_f32 v[72:73], v[72:73], v[132:133] op_sel_hi:[1,0]
	v_pk_mul_f32 v[64:65], v[64:65], v[100:101]
	v_pk_fma_f32 v[58:59], v[58:59], v[78:79], v[68:69]
	v_mov_b32_e32 v68, v52
	v_mov_b32_e32 v69, v54
	v_mov_b32_e32 v54, v53
	v_pk_mul_f32 v[72:73], v[72:73], v[102:103]
	v_pk_mul_f32 v[66:67], v[66:67], v[132:133] op_sel_hi:[1,0]
	v_pk_mul_f32 v[52:53], v[54:55], v[64:65]
	v_pk_mul_f32 v[64:65], v[68:69], v[64:65]
	v_pk_mul_f32 v[74:75], v[74:75], v[132:133] op_sel_hi:[1,0]
	v_pk_mul_f32 v[66:67], v[66:67], v[96:97]
	v_pk_fma_f32 v[54:55], v[54:55], v[72:73], v[64:65]
	v_mov_b32_e32 v65, v50
	v_mov_b32_e32 v50, v49
	v_pk_mul_f32 v[74:75], v[74:75], v[98:99]
	v_mov_b32_e32 v64, v48
	v_pk_mul_f32 v[48:49], v[50:51], v[66:67]
	v_pk_mul_f32 v[36:37], v[36:37], v[132:133] op_sel_hi:[1,0]
	v_pk_fma_f32 v[48:49], v[74:75], v[64:65], v[48:49] neg_lo:[0,0,1] neg_hi:[0,0,1]
	v_pk_mul_f32 v[64:65], v[64:65], v[66:67]
	v_pk_mul_f32 v[44:45], v[44:45], v[132:133] op_sel_hi:[1,0]
	v_pk_mul_f32 v[36:37], v[36:37], v[90:91]
	v_pk_fma_f32 v[50:51], v[50:51], v[74:75], v[64:65]
	v_mov_b32_e32 v64, v32
	v_mov_b32_e32 v65, v34
	v_mov_b32_e32 v34, v33
	v_pk_mul_f32 v[44:45], v[44:45], v[94:95]
	v_pk_mul_f32 v[38:39], v[38:39], v[132:133] op_sel_hi:[1,0]
	v_pk_mul_f32 v[32:33], v[36:37], v[34:35]
	v_pk_mul_f32 v[36:37], v[36:37], v[64:65]
	v_pk_mul_f32 v[46:47], v[46:47], v[132:133] op_sel_hi:[1,0]
	v_pk_mul_f32 v[38:39], v[38:39], v[86:87]
	v_pk_fma_f32 v[34:35], v[44:45], v[34:35], v[36:37]
	v_mov_b32_e32 v37, v26
	v_mov_b32_e32 v26, v25
	v_pk_mul_f32 v[46:47], v[46:47], v[92:93]
	v_mov_b32_e32 v36, v24
	v_pk_mul_f32 v[24:25], v[38:39], v[26:27]
	v_pk_mul_f32 v[28:29], v[28:29], v[132:133] op_sel_hi:[1,0]
	v_pk_fma_f32 v[24:25], v[46:47], v[36:37], v[24:25] neg_lo:[0,0,1] neg_hi:[0,0,1]
	v_pk_mul_f32 v[36:37], v[38:39], v[36:37]
	v_pk_mul_f32 v[40:41], v[40:41], v[132:133] op_sel_hi:[1,0]
	v_pk_mul_f32 v[28:29], v[28:29], v[82:83]
	v_pk_fma_f32 v[26:27], v[46:47], v[26:27], v[36:37]
	v_mov_b32_e32 v36, v20
	v_mov_b32_e32 v37, v22
	v_mov_b32_e32 v22, v21
	v_pk_mul_f32 v[40:41], v[40:41], v[88:89]
	v_pk_mul_f32 v[20:21], v[28:29], v[22:23]
	v_pk_mul_f32 v[28:29], v[28:29], v[36:37]
	v_pk_mul_f32 v[42:43], v[42:43], v[132:133] op_sel_hi:[1,0]
	v_pk_fma_f32 v[22:23], v[40:41], v[22:23], v[28:29]
	v_mov_b32_e32 v29, v18
	v_mov_b32_e32 v18, v17
	v_pk_mul_f32 v[42:43], v[42:43], v[84:85]
	v_mov_b32_e32 v28, v16
	v_pk_mul_f32 v[16:17], v[30:31], v[18:19]
	v_pk_fma_f32 v[60:61], v[80:81], v[76:77], v[60:61] neg_lo:[0,0,1] neg_hi:[0,0,1]
	v_pk_fma_f32 v[16:17], v[42:43], v[28:29], v[16:17] neg_lo:[0,0,1] neg_hi:[0,0,1]
	v_pk_mul_f32 v[28:29], v[30:31], v[28:29]
	v_pk_fma_f32 v[52:53], v[68:69], v[72:73], v[52:53] neg_lo:[0,0,1] neg_hi:[0,0,1]
	v_pk_fma_f32 v[32:33], v[44:45], v[64:65], v[32:33] neg_lo:[0,0,1] neg_hi:[0,0,1]
	v_pk_fma_f32 v[20:21], v[40:41], v[36:37], v[20:21] neg_lo:[0,0,1] neg_hi:[0,0,1]
	v_pk_fma_f32 v[18:19], v[42:43], v[18:19], v[28:29]
	v_cvt_pk_bf16_f32 v140, v60, v61
	v_cvt_pk_bf16_f32 v141, v56, v57
	v_cvt_pk_bf16_f32 v142, v52, v53
	v_cvt_pk_bf16_f32 v143, v48, v49
	v_cvt_pk_bf16_f32 v144, v62, v63
	v_cvt_pk_bf16_f32 v145, v58, v59
	v_cvt_pk_bf16_f32 v146, v54, v55
	v_cvt_pk_bf16_f32 v147, v50, v51
	v_cvt_pk_bf16_f32 v136, v32, v33
	v_cvt_pk_bf16_f32 v137, v24, v25
	v_cvt_pk_bf16_f32 v138, v20, v21
	v_cvt_pk_bf16_f32 v139, v16, v17
	v_cvt_pk_bf16_f32 v132, v34, v35
	v_cvt_pk_bf16_f32 v133, v26, v27
	v_cvt_pk_bf16_f32 v134, v22, v23
	v_cvt_pk_bf16_f32 v135, v18, v19
	v_mov_b32_e32 v64, 0
	v_mov_b32_e32 v65, 0
	v_mov_b32_e32 v66, 0
	v_mov_b32_e32 v67, 0
	v_mov_b32_e32 v68, 0
	v_mov_b32_e32 v69, 0
	v_mov_b32_e32 v70, 0
	v_mov_b32_e32 v71, 0
	v_mov_b32_e32 v72, 0
	v_mov_b32_e32 v73, 0
	v_mov_b32_e32 v74, 0
	v_mov_b32_e32 v75, 0
	v_mov_b32_e32 v76, 0
	v_mov_b32_e32 v77, 0
	v_mov_b32_e32 v78, 0
	v_mov_b32_e32 v79, 0
	v_mov_b32_e32 v48, 0
	v_mov_b32_e32 v49, 0
	v_mov_b32_e32 v50, 0
	v_mov_b32_e32 v51, 0
	v_mov_b32_e32 v52, 0
	v_mov_b32_e32 v53, 0
	v_mov_b32_e32 v54, 0
	v_mov_b32_e32 v55, 0
	v_mov_b32_e32 v56, 0
	v_mov_b32_e32 v57, 0
	v_mov_b32_e32 v58, 0
	v_mov_b32_e32 v59, 0
	v_mov_b32_e32 v60, 0
	v_mov_b32_e32 v61, 0
	v_mov_b32_e32 v62, 0
	v_mov_b32_e32 v63, 0
	v_mov_b32_e32 v32, 0
	v_mov_b32_e32 v33, 0
	v_mov_b32_e32 v34, 0
	v_mov_b32_e32 v35, 0
	v_mov_b32_e32 v36, 0
	v_mov_b32_e32 v37, 0
	v_mov_b32_e32 v38, 0
	v_mov_b32_e32 v39, 0
	v_mov_b32_e32 v40, 0
	v_mov_b32_e32 v41, 0
	v_mov_b32_e32 v42, 0
	v_mov_b32_e32 v43, 0
	v_mov_b32_e32 v44, 0
	v_mov_b32_e32 v45, 0
	v_mov_b32_e32 v46, 0
	v_mov_b32_e32 v47, 0
	v_mov_b32_e32 v16, 0
	v_mov_b32_e32 v17, 0
	v_mov_b32_e32 v18, 0
	v_mov_b32_e32 v19, 0
	v_mov_b32_e32 v20, 0
	v_mov_b32_e32 v21, 0
	v_mov_b32_e32 v22, 0
	v_mov_b32_e32 v23, 0
	v_mov_b32_e32 v24, 0
	v_mov_b32_e32 v25, 0
	v_mov_b32_e32 v26, 0
	v_mov_b32_e32 v27, 0
	v_mov_b32_e32 v28, 0
	v_mov_b32_e32 v29, 0
	v_mov_b32_e32 v30, 0
	v_mov_b32_e32 v31, 0
	v_mov_b32_e32 v80, 0xf149f2ca
	v_mov_b32_e32 v81, 0xf149f2ca
	v_mov_b32_e32 v82, 0xf149f2ca
	v_mov_b32_e32 v83, 0xf149f2ca
	v_mov_b32_e32 v84, 0xf149f2ca
	v_mov_b32_e32 v85, 0xf149f2ca
	v_mov_b32_e32 v86, 0xf149f2ca
	v_mov_b32_e32 v87, 0xf149f2ca
	v_mov_b32_e32 v88, 0xf149f2ca
	v_mov_b32_e32 v89, 0xf149f2ca
	v_mov_b32_e32 v90, 0xf149f2ca
	v_mov_b32_e32 v91, 0xf149f2ca
	v_mov_b32_e32 v92, 0xf149f2ca
	v_mov_b32_e32 v93, 0xf149f2ca
	v_mov_b32_e32 v94, 0xf149f2ca
	v_mov_b32_e32 v95, 0xf149f2ca
	v_mov_b32_e32 v225, 0
	v_mov_b32_e32 v166, 0
	v_mov_b32_e32 v175, 0
	v_mov_b32_e32 v202, 0
	s_waitcnt vmcnt(8)
	s_barrier
	ds_read_b128 v[112:115], v178
	ds_read_b128 v[116:119], v128
	ds_read_b128 v[120:123], v130
	ds_read_b128 v[124:127], v131
	s_mov_b32 s16, 0
